# P.V epilogue hx stores widened to dwordx4 (permlane32_swap + permlane16_swap on copies of each 8-byte piece), counted vmcnt waits of that epilogue re-derived for the new store count
# speedup vs baseline: 1.0175x; 1.0053x over previous
; __device__ __forceinline__ u32x2 pk4(f32x4 v) { u32x2 r; r.x = pk_bf16(v[0], v[1]); r.y = pk_bf16(v[2], v[3]); return r; }
; __device__ __forceinline__ f32x4 unpk4(u32x2 v) { return (f32x4){bf_lo(v.x), bf_hi(v.x), bf_lo(v.y), bf_hi(v.y)}; }
;     __device__ __forceinline__ void operator()(const f32x4 (&acc)[2][2][4][2], const Unit& u, int wr, int wc, int fr_in, int fq_in) const {
;     ...
;         const int w4 = wr * 4 + wc, lane = fq * 16 + fr;
; #pragma unroll
;         for (int ai = 0; ai < 2; ++ai) {
;             u32x2 z[4][2][2]; float rs[4];
; #pragma unroll
;             for (int m = 0; m < 4; ++m) {
;                 rs[m] = RSUM[(u.pm * 256 + ai * 128 + wr * 64 + m * 16 + fr) * 4 + u.pn];
; #pragma unroll
;                 for (int bj = 0; bj < 2; ++bj)
; #pragma unroll
;                     for (int n = 0; n < 2; ++n) z[m][bj][n] = __builtin_nontemporal_load((const u32x2*)SZXN + native_slot(u.pm, u.pn, w4, ai, m, bj, n, lane));
;             }
; #pragma unroll
;             for (int m = 0; m < 4; ++m) {
;                 const int row = u.pm * 256 + ai * 128 + wr * 64 + m * 16 + fr; const float inv = __builtin_amdgcn_rcpf(rs[m]);
; #pragma unroll
;                 for (int bj = 0; bj < 2; ++bj)
; #pragma unroll
;                     for (int n = 0; n < 2; ++n)
;                         *(u32x2*)(HX + (size_t)row * 1024 + u.pn * 256 + bj * 128 + wc * 32 + n * 16 + fq * 4) = pk4(unpk4(z[m][bj][n]) * (acc[ai][bj][m][n] * inv));
.LBB0_468:
	v_mbcnt_lo_u32_b32 v242, -1, 0
	v_mbcnt_hi_u32_b32 v242, -1, v242
	v_lshrrev_b32_e32 v242, 1, v242
	v_and_b32_e32 v242, 24, v242
	v_mov_b32_e32 v243, 0
	s_lshl_b32 s29, s28, 2
	s_add_i32 s60, s29, s78
	s_lshl_b32 s29, s28, 10
	v_mov_b32_e32 v142, v152
	v_mov_b32_e32 v143, v153
	s_add_i32 s29, s29, s43
	s_ashr_i32 s61, s60, 31
	v_lshl_add_u32 v136, v143, 4, v142
	v_lshl_add_u32 v159, v142, 2, s29
	v_ashrrev_i32_e32 v137, 31, v136
	v_add_u32_e32 v138, s78, v159
	v_lshl_add_u64 v[136:137], v[136:137], 3, s[92:93]
	v_ashrrev_i32_e32 v139, 31, v138
	s_lshl_b64 s[60:61], s[60:61], 17
	v_lshl_add_u64 v[138:139], v[138:139], 2, s[44:45]
	v_lshl_add_u64 v[136:137], v[136:137], 0, s[60:61]
	v_lshl_add_u64 v[140:141], v[136:137], 0, s[30:31]
	global_load_dword v188, v[138:139], off
	global_load_dwordx2 v[160:161], v[140:141], off nt
	global_load_dwordx2 v[162:163], v[140:141], off offset:512 nt
	global_load_dwordx2 v[164:165], v[140:141], off offset:1024 nt
	s_lshl_b32 s29, s28, 8
	s_add_i32 s53, s78, 64
	s_add_i32 s62, s29, s40
	v_add_u32_e32 v138, s62, v142
	v_add_u32_e32 v142, s53, v159
	global_load_dwordx2 v[166:167], v[140:141], off offset:1536 nt
	global_load_dwordx2 v[168:169], v[140:141], off offset:2048 nt
	v_lshlrev_b32_e32 v136, 2, v143
	v_ashrrev_i32_e32 v143, 31, v142
	v_lshl_add_u64 v[142:143], v[142:143], 2, s[44:45]
	global_load_dword v192, v[142:143], off
	global_load_dwordx2 v[170:171], v[140:141], off offset:2560 nt
	global_load_dwordx2 v[172:173], v[140:141], off offset:3072 nt
	s_add_i32 s60, s78, 0x80
	s_add_i32 s61, s78, 0xc0
	s_lshl_b32 s28, s78, 8
	v_ashrrev_i32_e32 v139, 31, v138
	s_ashr_i32 s29, s28, 31
	v_add_u32_e32 v144, s60, v159
	v_add_u32_e32 v146, s61, v159
	v_lshlrev_b64 v[142:143], 11, v[138:139]
	v_add_co_u32_e32 v174, vcc, s67, v140
	s_lshl_b64 s[28:29], s[28:29], 1
	v_ashrrev_i32_e32 v145, 31, v144
	v_ashrrev_i32_e32 v147, 31, v146
	v_lshl_add_u64 v[142:143], s[24:25], 0, v[142:143]
	v_addc_co_u32_e32 v175, vcc, 0, v141, vcc
	v_lshl_add_u64 v[144:145], v[144:145], 2, s[44:45]
	v_lshl_add_u64 v[146:147], v[146:147], 2, s[44:45]
	v_lshl_add_u64 v[148:149], v[142:143], 0, s[28:29]
	v_add_co_u32_e32 v142, vcc, s35, v140
	v_lshl_add_u64 v[176:177], v[148:149], 0, s[6:7]
	s_nop 0
	v_addc_co_u32_e32 v143, vcc, 0, v141, vcc
	global_load_dword v139, v[144:145], off
	global_load_dwordx2 v[178:179], v[174:175], off offset:512 nt
	global_load_dwordx2 v[180:181], v[140:141], off offset:3584 nt
	global_load_dwordx2 v[182:183], v[174:175], off offset:1024 nt
	global_load_dwordx2 v[184:185], v[174:175], off offset:1536 nt
	global_load_dwordx2 v[150:151], v[174:175], off offset:2048 nt
	global_load_dwordx2 v[148:149], v[174:175], off offset:2560 nt
	global_load_dwordx2 v[186:187], v[142:143], off offset:-4096 nt
	global_load_dword v193, v[146:147], off
	s_nop 0
	global_load_dwordx2 v[146:147], v[174:175], off offset:3072 nt
	global_load_dwordx2 v[144:145], v[174:175], off offset:3584 nt
	v_ashrrev_i32_e32 v137, 31, v136
	v_lshlrev_b64 v[136:137], 1, v[136:137]
	v_lshl_add_u64 v[174:175], v[176:177], 0, v[136:137]
	s_waitcnt vmcnt(0)
	v_rcp_f32_e32 v176, v188
	v_lshlrev_b32_e32 v188, 16, v160
	v_lshlrev_b32_e32 v190, 16, v162
	v_and_b32_e32 v191, 0xffff0000, v162
	v_lshlrev_b32_e32 v162, 16, v163
	v_and_b32_e32 v163, 0xffff0000, v163
	v_pk_mul_f32 v[120:121], v[120:121], v[176:177] op_sel_hi:[1,0]
	v_pk_mul_f32 v[122:123], v[122:123], v[176:177] op_sel_hi:[1,0]
	v_pk_mul_f32 v[120:121], v[120:121], v[190:191]
	v_pk_mul_f32 v[122:123], v[122:123], v[162:163]
	v_cvt_pk_bf16_f32 v120, v120, v121
	v_cvt_pk_bf16_f32 v121, v122, v123
	v_mov_b32_e32 v198, v120
	v_mov_b32_e32 v199, v121
	v_lshlrev_b32_e32 v120, 16, v164
	v_and_b32_e32 v121, 0xffff0000, v164
	v_lshlrev_b32_e32 v122, 16, v165
	v_and_b32_e32 v123, 0xffff0000, v165
	v_pk_mul_f32 v[116:117], v[116:117], v[176:177] op_sel_hi:[1,0]
	v_pk_mul_f32 v[118:119], v[118:119], v[176:177] op_sel_hi:[1,0]
	v_pk_mul_f32 v[116:117], v[116:117], v[120:121]
	v_pk_mul_f32 v[118:119], v[118:119], v[122:123]
	v_cvt_pk_bf16_f32 v116, v116, v117
	v_cvt_pk_bf16_f32 v117, v118, v119
	v_mov_b32_e32 v200, v116
	v_mov_b32_e32 v201, v117
	v_lshlrev_b32_e32 v116, 16, v166
	v_and_b32_e32 v117, 0xffff0000, v166
	v_lshlrev_b32_e32 v118, 16, v167
	v_and_b32_e32 v119, 0xffff0000, v167
	v_pk_mul_f32 v[112:113], v[112:113], v[176:177] op_sel_hi:[1,0]
	v_pk_mul_f32 v[114:115], v[114:115], v[176:177] op_sel_hi:[1,0]
	v_pk_mul_f32 v[112:113], v[112:113], v[116:117]
	v_pk_mul_f32 v[114:115], v[114:115], v[118:119]
	v_cvt_pk_bf16_f32 v112, v112, v113
	v_cvt_pk_bf16_f32 v113, v114, v115
	v_rcp_f32_e32 v114, v192
	v_mov_b32_e32 v202, v112
	v_mov_b32_e32 v203, v113
	v_add_u32_e32 v112, 16, v138
	v_ashrrev_i32_e32 v113, 31, v112
	v_lshlrev_b32_e32 v116, 16, v168
	v_and_b32_e32 v117, 0xffff0000, v168
	v_lshlrev_b32_e32 v118, 16, v169
	v_and_b32_e32 v119, 0xffff0000, v169
	v_pk_mul_f32 v[108:109], v[108:109], v[114:115] op_sel_hi:[1,0]
	v_pk_mul_f32 v[110:111], v[110:111], v[114:115] op_sel_hi:[1,0]
	v_lshlrev_b64 v[112:113], 11, v[112:113]
	v_pk_mul_f32 v[110:111], v[110:111], v[118:119]
	v_pk_mul_f32 v[108:109], v[108:109], v[116:117]
	v_pk_mul_f32 v[104:105], v[104:105], v[114:115] op_sel_hi:[1,0]
	v_cvt_pk_bf16_f32 v108, v108, v109
	v_cvt_pk_bf16_f32 v109, v110, v111
	v_lshl_add_u64 v[110:111], s[24:25], 0, v[112:113]
	v_lshl_add_u64 v[110:111], v[110:111], 0, s[28:29]
	v_lshl_add_u64 v[110:111], v[110:111], 0, s[6:7]
	v_lshl_add_u64 v[110:111], v[110:111], 0, v[136:137]
	v_mov_b32_e32 v204, v108
	v_mov_b32_e32 v205, v109
	v_lshlrev_b32_e32 v108, 16, v170
	v_and_b32_e32 v109, 0xffff0000, v170
; __device__ __forceinline__ u32x2 pk4(f32x4 v) { u32x2 r; r.x = pk_bf16(v[0], v[1]); r.y = pk_bf16(v[2], v[3]); return r; }
; __device__ __forceinline__ f32x4 unpk4(u32x2 v) { return (f32x4){bf_lo(v.x), bf_hi(v.x), bf_lo(v.y), bf_hi(v.y)}; }
;     __device__ __forceinline__ void operator()(const f32x4 (&acc)[2][2][4][2], const Unit& u, int wr, int wc, int fr_in, int fq_in) const {
;     ...
; #pragma unroll
;             for (int m = 0; m < 4; ++m) {
;                 const int row = u.pm * 256 + ai * 128 + wr * 64 + m * 16 + fr; const float inv = __builtin_amdgcn_rcpf(rs[m]);
; #pragma unroll
;                 for (int bj = 0; bj < 2; ++bj)
; #pragma unroll
;                     for (int n = 0; n < 2; ++n)
;                         *(u32x2*)(HX + (size_t)row * 1024 + u.pn * 256 + bj * 128 + wc * 32 + n * 16 + fq * 4) = pk4(unpk4(z[m][bj][n]) * (acc[ai][bj][m][n] * inv));
;             }
	v_lshlrev_b32_e32 v112, 16, v171
	v_and_b32_e32 v113, 0xffff0000, v171
	v_pk_mul_f32 v[106:107], v[106:107], v[114:115] op_sel_hi:[1,0]
	v_pk_mul_f32 v[104:105], v[104:105], v[108:109]
	v_pk_mul_f32 v[106:107], v[106:107], v[112:113]
	v_cvt_pk_bf16_f32 v104, v104, v105
	v_cvt_pk_bf16_f32 v105, v106, v107
	v_mov_b32_e32 v206, v104
	v_mov_b32_e32 v207, v105
	v_lshlrev_b32_e32 v104, 16, v172
	v_and_b32_e32 v105, 0xffff0000, v172
	v_lshlrev_b32_e32 v106, 16, v173
	v_and_b32_e32 v107, 0xffff0000, v173
	v_pk_mul_f32 v[100:101], v[100:101], v[114:115] op_sel_hi:[1,0]
	v_pk_mul_f32 v[102:103], v[102:103], v[114:115] op_sel_hi:[1,0]
	v_pk_mul_f32 v[100:101], v[100:101], v[104:105]
	v_pk_mul_f32 v[102:103], v[102:103], v[106:107]
	v_cvt_pk_bf16_f32 v100, v100, v101
	v_cvt_pk_bf16_f32 v101, v102, v103
	v_mov_b32_e32 v208, v100
	v_mov_b32_e32 v209, v101
	v_lshlrev_b32_e32 v100, 16, v180
	v_and_b32_e32 v101, 0xffff0000, v180
	v_lshlrev_b32_e32 v102, 16, v181
	v_and_b32_e32 v103, 0xffff0000, v181
	v_pk_mul_f32 v[96:97], v[96:97], v[114:115] op_sel_hi:[1,0]
	v_pk_mul_f32 v[98:99], v[98:99], v[114:115] op_sel_hi:[1,0]
	v_pk_mul_f32 v[96:97], v[96:97], v[100:101]
	v_pk_mul_f32 v[98:99], v[98:99], v[102:103]
	v_cvt_pk_bf16_f32 v96, v96, v97
	v_cvt_pk_bf16_f32 v97, v98, v99
	v_rcp_f32_e32 v98, v139
	v_mov_b32_e32 v210, v96
	v_mov_b32_e32 v211, v97
	s_nop 1
	v_permlane32_swap_b32_e32 v204, v206
	v_permlane32_swap_b32_e32 v205, v207
	v_permlane32_swap_b32_e32 v208, v210
	v_permlane32_swap_b32_e32 v209, v211
	v_permlane16_swap_b32_e32 v204, v206
	v_permlane16_swap_b32_e32 v205, v207
	v_permlane16_swap_b32_e32 v208, v210
	v_permlane16_swap_b32_e32 v209, v211
	v_lshl_add_u64 v[240:241], v[110:111], 0, v[242:243]
	global_store_dwordx4 v[240:241], v[204:207], off
	global_store_dwordx4 v[240:241], v[208:211], off offset:256
	v_add_u32_e32 v96, 32, v138
	v_ashrrev_i32_e32 v97, 31, v96
	v_lshlrev_b32_e32 v100, 16, v186
	v_and_b32_e32 v101, 0xffff0000, v186
	v_lshlrev_b32_e32 v102, 16, v187
	v_and_b32_e32 v103, 0xffff0000, v187
	v_pk_mul_f32 v[92:93], v[92:93], v[98:99] op_sel_hi:[1,0]
	v_pk_mul_f32 v[94:95], v[94:95], v[98:99] op_sel_hi:[1,0]
	v_lshlrev_b64 v[96:97], 11, v[96:97]
	v_pk_mul_f32 v[94:95], v[94:95], v[102:103]
	v_pk_mul_f32 v[92:93], v[92:93], v[100:101]
	v_pk_mul_f32 v[88:89], v[88:89], v[98:99] op_sel_hi:[1,0]
	v_cvt_pk_bf16_f32 v92, v92, v93
	v_cvt_pk_bf16_f32 v93, v94, v95
	v_lshl_add_u64 v[94:95], s[24:25], 0, v[96:97]
	v_lshl_add_u64 v[94:95], v[94:95], 0, s[28:29]
	v_lshl_add_u64 v[94:95], v[94:95], 0, s[6:7]
	v_lshl_add_u64 v[94:95], v[94:95], 0, v[136:137]
	v_mov_b32_e32 v212, v92
	v_mov_b32_e32 v213, v93
	v_lshlrev_b32_e32 v92, 16, v178
	v_and_b32_e32 v93, 0xffff0000, v178
	v_lshlrev_b32_e32 v96, 16, v179
	v_and_b32_e32 v97, 0xffff0000, v179
	v_pk_mul_f32 v[90:91], v[90:91], v[98:99] op_sel_hi:[1,0]
	v_pk_mul_f32 v[88:89], v[88:89], v[92:93]
	v_pk_mul_f32 v[90:91], v[90:91], v[96:97]
	v_cvt_pk_bf16_f32 v88, v88, v89
	v_cvt_pk_bf16_f32 v89, v90, v91
	v_mov_b32_e32 v214, v88
	v_mov_b32_e32 v215, v89
	v_lshlrev_b32_e32 v88, 16, v182
	v_and_b32_e32 v89, 0xffff0000, v182
	v_lshlrev_b32_e32 v90, 16, v183
	v_and_b32_e32 v91, 0xffff0000, v183
	v_pk_mul_f32 v[84:85], v[84:85], v[98:99] op_sel_hi:[1,0]
	v_pk_mul_f32 v[86:87], v[86:87], v[98:99] op_sel_hi:[1,0]
	v_pk_mul_f32 v[84:85], v[84:85], v[88:89]
	v_pk_mul_f32 v[86:87], v[86:87], v[90:91]
	v_cvt_pk_bf16_f32 v84, v84, v85
	v_cvt_pk_bf16_f32 v85, v86, v87
	v_mov_b32_e32 v216, v84
	v_mov_b32_e32 v217, v85
	v_lshlrev_b32_e32 v84, 16, v184
	v_and_b32_e32 v85, 0xffff0000, v184
	v_lshlrev_b32_e32 v86, 16, v185
	v_and_b32_e32 v87, 0xffff0000, v185
	v_pk_mul_f32 v[80:81], v[80:81], v[98:99] op_sel_hi:[1,0]
	v_pk_mul_f32 v[82:83], v[82:83], v[98:99] op_sel_hi:[1,0]
	v_pk_mul_f32 v[80:81], v[80:81], v[84:85]
	v_pk_mul_f32 v[82:83], v[82:83], v[86:87]
	v_cvt_pk_bf16_f32 v80, v80, v81
	v_cvt_pk_bf16_f32 v81, v82, v83
	v_rcp_f32_e32 v82, v193
	v_mov_b32_e32 v218, v80
	v_mov_b32_e32 v219, v81
	s_nop 1
	v_permlane32_swap_b32_e32 v212, v214
	v_permlane32_swap_b32_e32 v213, v215
	v_permlane32_swap_b32_e32 v216, v218
	v_permlane32_swap_b32_e32 v217, v219
	v_permlane16_swap_b32_e32 v212, v214
	v_permlane16_swap_b32_e32 v213, v215
	v_permlane16_swap_b32_e32 v216, v218
	v_permlane16_swap_b32_e32 v217, v219
	v_lshl_add_u64 v[240:241], v[94:95], 0, v[242:243]
	global_store_dwordx4 v[240:241], v[212:215], off
	global_store_dwordx4 v[240:241], v[216:219], off offset:256
	v_add_u32_e32 v80, 48, v138
	v_ashrrev_i32_e32 v81, 31, v80
	v_lshlrev_b32_e32 v84, 16, v150
	v_and_b32_e32 v85, 0xffff0000, v150
	v_lshlrev_b32_e32 v86, 16, v151
	v_and_b32_e32 v87, 0xffff0000, v151
	v_pk_mul_f32 v[76:77], v[76:77], v[82:83] op_sel_hi:[1,0]
	v_pk_mul_f32 v[78:79], v[78:79], v[82:83] op_sel_hi:[1,0]
	v_lshlrev_b64 v[80:81], 11, v[80:81]
	v_pk_mul_f32 v[78:79], v[78:79], v[86:87]
	v_pk_mul_f32 v[76:77], v[76:77], v[84:85]
	v_pk_mul_f32 v[72:73], v[72:73], v[82:83] op_sel_hi:[1,0]
	v_cvt_pk_bf16_f32 v76, v76, v77
	v_cvt_pk_bf16_f32 v77, v78, v79
	v_lshl_add_u64 v[78:79], s[24:25], 0, v[80:81]
	v_lshl_add_u64 v[78:79], v[78:79], 0, s[28:29]
	v_lshl_add_u64 v[78:79], v[78:79], 0, s[6:7]
	v_lshl_add_u64 v[78:79], v[78:79], 0, v[136:137]
	v_mov_b32_e32 v224, v76
	v_mov_b32_e32 v225, v77
	v_lshlrev_b32_e32 v76, 16, v148
	v_and_b32_e32 v77, 0xffff0000, v148
	v_lshlrev_b32_e32 v80, 16, v149
	v_and_b32_e32 v81, 0xffff0000, v149
	v_pk_mul_f32 v[74:75], v[74:75], v[82:83] op_sel_hi:[1,0]
	v_pk_mul_f32 v[72:73], v[72:73], v[76:77]
	v_pk_mul_f32 v[74:75], v[74:75], v[80:81]
	v_cvt_pk_bf16_f32 v72, v72, v73
	v_cvt_pk_bf16_f32 v73, v74, v75
; __device__ __forceinline__ u32x2 pk4(f32x4 v) { u32x2 r; r.x = pk_bf16(v[0], v[1]); r.y = pk_bf16(v[2], v[3]); return r; }
; __device__ __forceinline__ f32x4 unpk4(u32x2 v) { return (f32x4){bf_lo(v.x), bf_hi(v.x), bf_lo(v.y), bf_hi(v.y)}; }
;     __device__ __forceinline__ void operator()(const f32x4 (&acc)[2][2][4][2], const Unit& u, int wr, int wc, int fr_in, int fq_in) const {
;     ...
;         for (int ai = 0; ai < 2; ++ai) {
;             u32x2 z[4][2][2]; float rs[4];
; #pragma unroll
;             for (int m = 0; m < 4; ++m) {
;                 rs[m] = RSUM[(u.pm * 256 + ai * 128 + wr * 64 + m * 16 + fr) * 4 + u.pn];
; #pragma unroll
;                 for (int bj = 0; bj < 2; ++bj)
; #pragma unroll
;                     for (int n = 0; n < 2; ++n) z[m][bj][n] = __builtin_nontemporal_load((const u32x2*)SZXN + native_slot(u.pm, u.pn, w4, ai, m, bj, n, lane));
;             }
; #pragma unroll
;             for (int m = 0; m < 4; ++m) {
;                 const int row = u.pm * 256 + ai * 128 + wr * 64 + m * 16 + fr; const float inv = __builtin_amdgcn_rcpf(rs[m]);
; #pragma unroll
;                 for (int bj = 0; bj < 2; ++bj)
; #pragma unroll
;                     for (int n = 0; n < 2; ++n)
;                         *(u32x2*)(HX + (size_t)row * 1024 + u.pn * 256 + bj * 128 + wc * 32 + n * 16 + fq * 4) = pk4(unpk4(z[m][bj][n]) * (acc[ai][bj][m][n] * inv));
;             }
	v_mov_b32_e32 v226, v72
	v_mov_b32_e32 v227, v73
	v_lshlrev_b32_e32 v72, 16, v146
	v_and_b32_e32 v73, 0xffff0000, v146
	v_lshlrev_b32_e32 v74, 16, v147
	v_and_b32_e32 v75, 0xffff0000, v147
	v_pk_mul_f32 v[68:69], v[68:69], v[82:83] op_sel_hi:[1,0]
	v_pk_mul_f32 v[70:71], v[70:71], v[82:83] op_sel_hi:[1,0]
	v_pk_mul_f32 v[68:69], v[68:69], v[72:73]
	v_pk_mul_f32 v[70:71], v[70:71], v[74:75]
	v_cvt_pk_bf16_f32 v68, v68, v69
	v_cvt_pk_bf16_f32 v69, v70, v71
	v_mov_b32_e32 v228, v68
	v_mov_b32_e32 v229, v69
	v_lshlrev_b32_e32 v68, 16, v144
	v_and_b32_e32 v69, 0xffff0000, v144
	v_lshlrev_b32_e32 v70, 16, v145
	v_and_b32_e32 v71, 0xffff0000, v145
	v_pk_mul_f32 v[64:65], v[64:65], v[82:83] op_sel_hi:[1,0]
	v_pk_mul_f32 v[66:67], v[66:67], v[82:83] op_sel_hi:[1,0]
	v_pk_mul_f32 v[64:65], v[64:65], v[68:69]
	v_pk_mul_f32 v[66:67], v[66:67], v[70:71]
	v_and_b32_e32 v189, 0xffff0000, v160
	v_lshlrev_b32_e32 v160, 16, v161
	v_and_b32_e32 v161, 0xffff0000, v161
	v_pk_mul_f32 v[124:125], v[124:125], v[176:177] op_sel_hi:[1,0]
	v_pk_mul_f32 v[126:127], v[126:127], v[176:177] op_sel_hi:[1,0]
	v_cvt_pk_bf16_f32 v64, v64, v65
	v_cvt_pk_bf16_f32 v65, v66, v67
	v_add_u32_e32 v66, 0x200, v159
	v_pk_mul_f32 v[126:127], v[126:127], v[160:161]
	v_pk_mul_f32 v[124:125], v[124:125], v[188:189]
	v_mov_b32_e32 v230, v64
	v_mov_b32_e32 v231, v65
	s_nop 1
	v_permlane32_swap_b32_e32 v224, v226
	v_permlane32_swap_b32_e32 v225, v227
	v_permlane32_swap_b32_e32 v228, v230
	v_permlane32_swap_b32_e32 v229, v231
	v_permlane16_swap_b32_e32 v224, v226
	v_permlane16_swap_b32_e32 v225, v227
	v_permlane16_swap_b32_e32 v228, v230
	v_permlane16_swap_b32_e32 v229, v231
	v_lshl_add_u64 v[240:241], v[78:79], 0, v[242:243]
	global_store_dwordx4 v[240:241], v[224:227], off
	global_store_dwordx4 v[240:241], v[228:231], off offset:256
	v_add_u32_e32 v64, s78, v66
	v_cvt_pk_bf16_f32 v124, v124, v125
	v_cvt_pk_bf16_f32 v125, v126, v127
	v_ashrrev_i32_e32 v65, 31, v64
	v_mov_b32_e32 v196, v124
	v_mov_b32_e32 v197, v125
	s_nop 1
	v_permlane32_swap_b32_e32 v196, v198
	v_permlane32_swap_b32_e32 v197, v199
	v_permlane32_swap_b32_e32 v200, v202
	v_permlane32_swap_b32_e32 v201, v203
	v_permlane16_swap_b32_e32 v196, v198
	v_permlane16_swap_b32_e32 v197, v199
	v_permlane16_swap_b32_e32 v200, v202
	v_permlane16_swap_b32_e32 v201, v203
	v_lshl_add_u64 v[240:241], v[174:175], 0, v[242:243]
	global_store_dwordx4 v[240:241], v[196:199], off
	global_store_dwordx4 v[240:241], v[200:203], off offset:256
	v_lshl_add_u64 v[64:65], v[64:65], 2, s[44:45]
	global_load_dword v98, v[64:65], off
	global_load_dwordx2 v[72:73], v[142:143], off nt
	global_load_dwordx2 v[74:75], v[142:143], off offset:512 nt
	global_load_dwordx2 v[76:77], v[142:143], off offset:1024 nt
	global_load_dwordx2 v[78:79], v[142:143], off offset:1536 nt
	v_add_u32_e32 v64, s53, v66
	v_ashrrev_i32_e32 v65, 31, v64
	v_lshl_add_u64 v[64:65], v[64:65], 2, s[44:45]
	global_load_dword v99, v[64:65], off
	global_load_dwordx2 v[80:81], v[142:143], off offset:2048 nt
	global_load_dwordx2 v[82:83], v[142:143], off offset:2560 nt
	global_load_dwordx2 v[84:85], v[142:143], off offset:3072 nt
	global_load_dwordx2 v[86:87], v[142:143], off offset:3584 nt
	v_add_u32_e32 v64, s60, v66
	v_ashrrev_i32_e32 v65, 31, v64
	v_lshl_add_u64 v[64:65], v[64:65], 2, s[44:45]
	v_add_co_u32_e32 v88, vcc, s68, v140
	s_waitcnt vmcnt(9)
	v_rcp_f32_e32 v98, v98
	v_addc_co_u32_e32 v89, vcc, 0, v141, vcc
	global_load_dword v102, v[64:65], off
	global_load_dwordx2 v[90:91], v[88:89], off nt
	v_add_u32_e32 v64, s61, v66
	v_ashrrev_i32_e32 v65, 31, v64
	v_lshl_add_u64 v[64:65], v[64:65], 2, s[44:45]
	global_load_dwordx2 v[92:93], v[88:89], off offset:512 nt
	global_load_dwordx2 v[94:95], v[88:89], off offset:1024 nt
	global_load_dwordx2 v[96:97], v[88:89], off offset:1536 nt
	global_load_dwordx2 v[70:71], v[88:89], off offset:2048 nt
	global_load_dword v103, v[64:65], off
	global_load_dwordx2 v[68:69], v[88:89], off offset:2560 nt
	global_load_dwordx2 v[66:67], v[88:89], off offset:3072 nt
	s_nop 0
	global_load_dwordx2 v[64:65], v[88:89], off offset:3584 nt
	v_add_u32_e32 v88, 0x80, v138
	v_ashrrev_i32_e32 v89, 31, v88
	s_waitcnt vmcnt(18)
	v_lshlrev_b32_e32 v100, 16, v72
	v_and_b32_e32 v101, 0xffff0000, v72
	v_lshlrev_b32_e32 v72, 16, v73
	v_and_b32_e32 v73, 0xffff0000, v73
	s_waitcnt vmcnt(14)
	v_pk_mul_f32 v[60:61], v[60:61], v[98:99] op_sel_hi:[1,0]
	v_pk_mul_f32 v[62:63], v[62:63], v[98:99] op_sel_hi:[1,0]
	v_lshlrev_b64 v[88:89], 11, v[88:89]
	v_pk_mul_f32 v[62:63], v[62:63], v[72:73]
	v_pk_mul_f32 v[60:61], v[60:61], v[100:101]
	v_lshlrev_b32_e32 v72, 16, v75
	v_cvt_pk_bf16_f32 v60, v60, v61
	v_cvt_pk_bf16_f32 v61, v62, v63
	v_lshl_add_u64 v[62:63], s[24:25], 0, v[88:89]
	v_lshl_add_u64 v[62:63], v[62:63], 0, s[28:29]
	v_lshl_add_u64 v[62:63], v[62:63], 0, s[6:7]
	v_lshl_add_u64 v[62:63], v[62:63], 0, v[136:137]
	v_mov_b32_e32 v232, v60
	v_mov_b32_e32 v233, v61
	v_lshlrev_b32_e32 v60, 16, v74
	v_and_b32_e32 v61, 0xffff0000, v74
	v_and_b32_e32 v73, 0xffff0000, v75
	v_pk_mul_f32 v[56:57], v[56:57], v[98:99] op_sel_hi:[1,0]
	v_pk_mul_f32 v[58:59], v[58:59], v[98:99] op_sel_hi:[1,0]
	v_pk_mul_f32 v[56:57], v[56:57], v[60:61]
	v_pk_mul_f32 v[58:59], v[58:59], v[72:73]
	v_cvt_pk_bf16_f32 v56, v56, v57
	v_cvt_pk_bf16_f32 v57, v58, v59
	v_mov_b32_e32 v234, v56
	v_mov_b32_e32 v235, v57
	v_lshlrev_b32_e32 v56, 16, v76
	v_and_b32_e32 v57, 0xffff0000, v76
	v_lshlrev_b32_e32 v58, 16, v77
	v_and_b32_e32 v59, 0xffff0000, v77
	v_pk_mul_f32 v[52:53], v[52:53], v[98:99] op_sel_hi:[1,0]
	v_pk_mul_f32 v[54:55], v[54:55], v[98:99] op_sel_hi:[1,0]
	v_pk_mul_f32 v[52:53], v[52:53], v[56:57]
	v_pk_mul_f32 v[54:55], v[54:55], v[58:59]
	v_cvt_pk_bf16_f32 v52, v52, v53
	v_cvt_pk_bf16_f32 v53, v54, v55
	v_mov_b32_e32 v236, v52
	v_mov_b32_e32 v237, v53
	v_lshlrev_b32_e32 v52, 16, v78
	v_and_b32_e32 v53, 0xffff0000, v78
	v_lshlrev_b32_e32 v54, 16, v79
	v_and_b32_e32 v55, 0xffff0000, v79
	v_pk_mul_f32 v[48:49], v[48:49], v[98:99] op_sel_hi:[1,0]
	v_pk_mul_f32 v[50:51], v[50:51], v[98:99] op_sel_hi:[1,0]
	v_pk_mul_f32 v[48:49], v[48:49], v[52:53]
	v_pk_mul_f32 v[50:51], v[50:51], v[54:55]
	v_cvt_pk_bf16_f32 v48, v48, v49
	v_cvt_pk_bf16_f32 v49, v50, v51
	v_rcp_f32_e32 v50, v99
	v_mov_b32_e32 v238, v48
	v_mov_b32_e32 v239, v49
	s_nop 1
	v_permlane32_swap_b32_e32 v232, v234
	v_permlane32_swap_b32_e32 v233, v235
	v_permlane32_swap_b32_e32 v236, v238
	v_permlane32_swap_b32_e32 v237, v239
	v_permlane16_swap_b32_e32 v232, v234
	v_permlane16_swap_b32_e32 v233, v235
	v_permlane16_swap_b32_e32 v236, v238
	v_permlane16_swap_b32_e32 v237, v239
	v_lshl_add_u64 v[240:241], v[62:63], 0, v[242:243]
	global_store_dwordx4 v[240:241], v[232:235], off
	global_store_dwordx4 v[240:241], v[236:239], off offset:256
	v_add_u32_e32 v48, 0x90, v138
	v_ashrrev_i32_e32 v49, 31, v48
	s_waitcnt vmcnt(15)
; __device__ __forceinline__ u32x2 pk4(f32x4 v) { u32x2 r; r.x = pk_bf16(v[0], v[1]); r.y = pk_bf16(v[2], v[3]); return r; }
; __device__ __forceinline__ f32x4 unpk4(u32x2 v) { return (f32x4){bf_lo(v.x), bf_hi(v.x), bf_lo(v.y), bf_hi(v.y)}; }
;     __device__ __forceinline__ void operator()(const f32x4 (&acc)[2][2][4][2], const Unit& u, int wr, int wc, int fr_in, int fq_in) const {
;     ...
; #pragma unroll
;             for (int m = 0; m < 4; ++m) {
;                 const int row = u.pm * 256 + ai * 128 + wr * 64 + m * 16 + fr; const float inv = __builtin_amdgcn_rcpf(rs[m]);
; #pragma unroll
;                 for (int bj = 0; bj < 2; ++bj)
; #pragma unroll
;                     for (int n = 0; n < 2; ++n)
;                         *(u32x2*)(HX + (size_t)row * 1024 + u.pn * 256 + bj * 128 + wc * 32 + n * 16 + fq * 4) = pk4(unpk4(z[m][bj][n]) * (acc[ai][bj][m][n] * inv));
;             }
	v_lshlrev_b32_e32 v52, 16, v80
	v_and_b32_e32 v53, 0xffff0000, v80
	v_lshlrev_b32_e32 v54, 16, v81
	v_and_b32_e32 v55, 0xffff0000, v81
	v_pk_mul_f32 v[44:45], v[44:45], v[50:51] op_sel_hi:[1,0]
	v_pk_mul_f32 v[46:47], v[46:47], v[50:51] op_sel_hi:[1,0]
	v_lshlrev_b64 v[48:49], 11, v[48:49]
	v_pk_mul_f32 v[46:47], v[46:47], v[54:55]
	v_pk_mul_f32 v[44:45], v[44:45], v[52:53]
	v_pk_mul_f32 v[40:41], v[40:41], v[50:51] op_sel_hi:[1,0]
	v_cvt_pk_bf16_f32 v44, v44, v45
	v_cvt_pk_bf16_f32 v45, v46, v47
	v_lshl_add_u64 v[46:47], s[24:25], 0, v[48:49]
	v_lshl_add_u64 v[46:47], v[46:47], 0, s[28:29]
	v_lshl_add_u64 v[46:47], v[46:47], 0, s[6:7]
	v_lshl_add_u64 v[46:47], v[46:47], 0, v[136:137]
	v_mov_b32_e32 v204, v44
	v_mov_b32_e32 v205, v45
	s_waitcnt vmcnt(14)
	v_lshlrev_b32_e32 v44, 16, v82
	v_and_b32_e32 v45, 0xffff0000, v82
	v_lshlrev_b32_e32 v48, 16, v83
	v_and_b32_e32 v49, 0xffff0000, v83
	v_pk_mul_f32 v[42:43], v[42:43], v[50:51] op_sel_hi:[1,0]
	v_pk_mul_f32 v[40:41], v[40:41], v[44:45]
	v_pk_mul_f32 v[42:43], v[42:43], v[48:49]
	v_cvt_pk_bf16_f32 v40, v40, v41
	v_cvt_pk_bf16_f32 v41, v42, v43
	v_mov_b32_e32 v206, v40
	v_mov_b32_e32 v207, v41
	s_waitcnt vmcnt(13)
	v_lshlrev_b32_e32 v40, 16, v84
	v_and_b32_e32 v41, 0xffff0000, v84
	v_lshlrev_b32_e32 v42, 16, v85
	v_and_b32_e32 v43, 0xffff0000, v85
	v_pk_mul_f32 v[36:37], v[36:37], v[50:51] op_sel_hi:[1,0]
	v_pk_mul_f32 v[38:39], v[38:39], v[50:51] op_sel_hi:[1,0]
	v_pk_mul_f32 v[36:37], v[36:37], v[40:41]
	v_pk_mul_f32 v[38:39], v[38:39], v[42:43]
	v_cvt_pk_bf16_f32 v36, v36, v37
	v_cvt_pk_bf16_f32 v37, v38, v39
	v_mov_b32_e32 v208, v36
	v_mov_b32_e32 v209, v37
	s_waitcnt vmcnt(12)
	v_lshlrev_b32_e32 v36, 16, v86
	v_and_b32_e32 v37, 0xffff0000, v86
	v_lshlrev_b32_e32 v38, 16, v87
	v_and_b32_e32 v39, 0xffff0000, v87
	v_pk_mul_f32 v[32:33], v[32:33], v[50:51] op_sel_hi:[1,0]
	v_pk_mul_f32 v[34:35], v[34:35], v[50:51] op_sel_hi:[1,0]
	v_pk_mul_f32 v[32:33], v[32:33], v[36:37]
	v_pk_mul_f32 v[34:35], v[34:35], v[38:39]
	v_cvt_pk_bf16_f32 v32, v32, v33
	v_cvt_pk_bf16_f32 v33, v34, v35
	s_waitcnt vmcnt(11)
	v_rcp_f32_e32 v34, v102
	v_mov_b32_e32 v210, v32
	v_mov_b32_e32 v211, v33
	s_nop 1
	v_permlane32_swap_b32_e32 v204, v206
	v_permlane32_swap_b32_e32 v205, v207
	v_permlane32_swap_b32_e32 v208, v210
	v_permlane32_swap_b32_e32 v209, v211
	v_permlane16_swap_b32_e32 v204, v206
	v_permlane16_swap_b32_e32 v205, v207
	v_permlane16_swap_b32_e32 v208, v210
	v_permlane16_swap_b32_e32 v209, v211
	v_lshl_add_u64 v[240:241], v[46:47], 0, v[242:243]
	global_store_dwordx4 v[240:241], v[204:207], off
	global_store_dwordx4 v[240:241], v[208:211], off offset:256
	v_add_u32_e32 v32, 0xa0, v138
	v_ashrrev_i32_e32 v33, 31, v32
	s_waitcnt vmcnt(12)
	v_lshlrev_b32_e32 v36, 16, v90
	v_and_b32_e32 v37, 0xffff0000, v90
	v_lshlrev_b32_e32 v38, 16, v91
	v_and_b32_e32 v39, 0xffff0000, v91
	v_pk_mul_f32 v[28:29], v[28:29], v[34:35] op_sel_hi:[1,0]
	v_pk_mul_f32 v[30:31], v[30:31], v[34:35] op_sel_hi:[1,0]
	v_lshlrev_b64 v[32:33], 11, v[32:33]
	v_pk_mul_f32 v[30:31], v[30:31], v[38:39]
	v_pk_mul_f32 v[28:29], v[28:29], v[36:37]
	v_pk_mul_f32 v[24:25], v[24:25], v[34:35] op_sel_hi:[1,0]
	v_cvt_pk_bf16_f32 v28, v28, v29
	v_cvt_pk_bf16_f32 v29, v30, v31
	v_lshl_add_u64 v[30:31], s[24:25], 0, v[32:33]
	v_lshl_add_u64 v[30:31], v[30:31], 0, s[28:29]
	v_lshl_add_u64 v[30:31], v[30:31], 0, s[6:7]
	v_lshl_add_u64 v[30:31], v[30:31], 0, v[136:137]
	v_mov_b32_e32 v212, v28
	v_mov_b32_e32 v213, v29
	s_waitcnt vmcnt(11)
	v_lshlrev_b32_e32 v28, 16, v92
	v_and_b32_e32 v29, 0xffff0000, v92
	v_lshlrev_b32_e32 v32, 16, v93
	v_and_b32_e32 v33, 0xffff0000, v93
	v_pk_mul_f32 v[26:27], v[26:27], v[34:35] op_sel_hi:[1,0]
	v_pk_mul_f32 v[24:25], v[24:25], v[28:29]
	v_pk_mul_f32 v[26:27], v[26:27], v[32:33]
	v_cvt_pk_bf16_f32 v24, v24, v25
	v_cvt_pk_bf16_f32 v25, v26, v27
	v_mov_b32_e32 v214, v24
	v_mov_b32_e32 v215, v25
	s_waitcnt vmcnt(10)
; __device__ __forceinline__ u32x2 pk4(f32x4 v) { u32x2 r; r.x = pk_bf16(v[0], v[1]); r.y = pk_bf16(v[2], v[3]); return r; }
; __device__ __forceinline__ f32x4 unpk4(u32x2 v) { return (f32x4){bf_lo(v.x), bf_hi(v.x), bf_lo(v.y), bf_hi(v.y)}; }
;     __device__ __forceinline__ void operator()(const f32x4 (&acc)[2][2][4][2], const Unit& u, int wr, int wc, int fr_in, int fq_in) const {
;     ...
; #pragma unroll
;             for (int m = 0; m < 4; ++m) {
;                 const int row = u.pm * 256 + ai * 128 + wr * 64 + m * 16 + fr; const float inv = __builtin_amdgcn_rcpf(rs[m]);
; #pragma unroll
;                 for (int bj = 0; bj < 2; ++bj)
; #pragma unroll
;                     for (int n = 0; n < 2; ++n)
;                         *(u32x2*)(HX + (size_t)row * 1024 + u.pn * 256 + bj * 128 + wc * 32 + n * 16 + fq * 4) = pk4(unpk4(z[m][bj][n]) * (acc[ai][bj][m][n] * inv));
;             }
	v_lshlrev_b32_e32 v24, 16, v94
	v_and_b32_e32 v25, 0xffff0000, v94
	v_lshlrev_b32_e32 v26, 16, v95
	v_and_b32_e32 v27, 0xffff0000, v95
	v_pk_mul_f32 v[20:21], v[20:21], v[34:35] op_sel_hi:[1,0]
	v_pk_mul_f32 v[22:23], v[22:23], v[34:35] op_sel_hi:[1,0]
	v_pk_mul_f32 v[20:21], v[20:21], v[24:25]
	v_pk_mul_f32 v[22:23], v[22:23], v[26:27]
	v_cvt_pk_bf16_f32 v20, v20, v21
	v_cvt_pk_bf16_f32 v21, v22, v23
	v_mov_b32_e32 v216, v20
	v_mov_b32_e32 v217, v21
	s_waitcnt vmcnt(9)
	v_lshlrev_b32_e32 v20, 16, v96
	v_and_b32_e32 v21, 0xffff0000, v96
	v_lshlrev_b32_e32 v22, 16, v97
	v_and_b32_e32 v23, 0xffff0000, v97
	v_pk_mul_f32 v[16:17], v[16:17], v[34:35] op_sel_hi:[1,0]
	v_pk_mul_f32 v[18:19], v[18:19], v[34:35] op_sel_hi:[1,0]
	v_pk_mul_f32 v[16:17], v[16:17], v[20:21]
	v_pk_mul_f32 v[18:19], v[18:19], v[22:23]
	v_cvt_pk_bf16_f32 v16, v16, v17
	v_cvt_pk_bf16_f32 v17, v18, v19
	s_waitcnt vmcnt(7)
	v_rcp_f32_e32 v18, v103
	v_mov_b32_e32 v218, v16
	v_mov_b32_e32 v219, v17
	s_nop 1
	v_permlane32_swap_b32_e32 v212, v214
	v_permlane32_swap_b32_e32 v213, v215
	v_permlane32_swap_b32_e32 v216, v218
	v_permlane32_swap_b32_e32 v217, v219
	v_permlane16_swap_b32_e32 v212, v214
	v_permlane16_swap_b32_e32 v213, v215
	v_permlane16_swap_b32_e32 v216, v218
	v_permlane16_swap_b32_e32 v217, v219
	v_lshl_add_u64 v[240:241], v[30:31], 0, v[242:243]
	global_store_dwordx4 v[240:241], v[212:215], off
	global_store_dwordx4 v[240:241], v[216:219], off offset:256
	v_add_u32_e32 v16, 0xb0, v138
	v_ashrrev_i32_e32 v17, 31, v16
	v_lshlrev_b32_e32 v20, 16, v70
	v_and_b32_e32 v21, 0xffff0000, v70
	v_lshlrev_b32_e32 v22, 16, v71
	v_and_b32_e32 v23, 0xffff0000, v71
	v_pk_mul_f32 v[12:13], v[12:13], v[18:19] op_sel_hi:[1,0]
	v_pk_mul_f32 v[14:15], v[14:15], v[18:19] op_sel_hi:[1,0]
	v_lshlrev_b64 v[16:17], 11, v[16:17]
	v_pk_mul_f32 v[14:15], v[14:15], v[22:23]
	v_pk_mul_f32 v[12:13], v[12:13], v[20:21]
	v_pk_mul_f32 v[8:9], v[8:9], v[18:19] op_sel_hi:[1,0]
	v_cvt_pk_bf16_f32 v12, v12, v13
	v_cvt_pk_bf16_f32 v13, v14, v15
	v_lshl_add_u64 v[14:15], s[24:25], 0, v[16:17]
	v_lshl_add_u64 v[14:15], v[14:15], 0, s[28:29]
	v_lshl_add_u64 v[14:15], v[14:15], 0, s[6:7]
	v_lshl_add_u64 v[14:15], v[14:15], 0, v[136:137]
	v_mov_b32_e32 v224, v12
	v_mov_b32_e32 v225, v13
	s_waitcnt vmcnt(8)
	v_lshlrev_b32_e32 v12, 16, v68
	v_and_b32_e32 v13, 0xffff0000, v68
	v_lshlrev_b32_e32 v16, 16, v69
	v_and_b32_e32 v17, 0xffff0000, v69
	v_pk_mul_f32 v[10:11], v[10:11], v[18:19] op_sel_hi:[1,0]
	v_pk_mul_f32 v[8:9], v[8:9], v[12:13]
	v_pk_mul_f32 v[10:11], v[10:11], v[16:17]
	v_cvt_pk_bf16_f32 v8, v8, v9
	v_cvt_pk_bf16_f32 v9, v10, v11
	v_mov_b32_e32 v226, v8
	v_mov_b32_e32 v227, v9
	s_waitcnt vmcnt(7)
	v_lshlrev_b32_e32 v8, 16, v66
	v_and_b32_e32 v9, 0xffff0000, v66
	v_lshlrev_b32_e32 v10, 16, v67
	v_and_b32_e32 v11, 0xffff0000, v67
	v_pk_mul_f32 v[4:5], v[4:5], v[18:19] op_sel_hi:[1,0]
	v_pk_mul_f32 v[6:7], v[6:7], v[18:19] op_sel_hi:[1,0]
	v_pk_mul_f32 v[4:5], v[4:5], v[8:9]
	v_pk_mul_f32 v[6:7], v[6:7], v[10:11]
	v_cvt_pk_bf16_f32 v4, v4, v5
	v_cvt_pk_bf16_f32 v5, v6, v7
	v_mov_b32_e32 v228, v4
	v_mov_b32_e32 v229, v5
	s_waitcnt vmcnt(6)
	v_lshlrev_b32_e32 v4, 16, v64
	v_and_b32_e32 v5, 0xffff0000, v64
	v_lshlrev_b32_e32 v6, 16, v65
	v_and_b32_e32 v7, 0xffff0000, v65
	v_pk_mul_f32 v[0:1], v[0:1], v[18:19] op_sel_hi:[1,0]
	v_pk_mul_f32 v[2:3], v[2:3], v[18:19] op_sel_hi:[1,0]
	v_pk_mul_f32 v[0:1], v[0:1], v[4:5]
	v_pk_mul_f32 v[2:3], v[2:3], v[6:7]
	v_cvt_pk_bf16_f32 v0, v0, v1
	v_cvt_pk_bf16_f32 v1, v2, v3
	s_andn2_b64 vcc, exec, s[58:59]
	s_mov_b64 s[28:29], -1
	v_mov_b32_e32 v230, v0
	v_mov_b32_e32 v231, v1
	s_nop 1
	v_permlane32_swap_b32_e32 v224, v226
	v_permlane32_swap_b32_e32 v225, v227
	v_permlane32_swap_b32_e32 v228, v230
	v_permlane32_swap_b32_e32 v229, v231
	v_permlane16_swap_b32_e32 v224, v226
	v_permlane16_swap_b32_e32 v225, v227
	v_permlane16_swap_b32_e32 v228, v230
	v_permlane16_swap_b32_e32 v229, v231
	v_lshl_add_u64 v[240:241], v[14:15], 0, v[242:243]
	global_store_dwordx4 v[240:241], v[224:227], off
	global_store_dwordx4 v[240:241], v[228:231], off offset:256
	s_cbranch_vccnz .LBB0_463
	s_andn2_b64 vcc, exec, s[8:9]
	s_cbranch_vccnz .LBB0_462
	s_barrier
	s_branch .LBB0_462
